# SwiGLU epilogue: packed-f32 (v_pk_mul/v_pk_fma) for the plain multiplies, on top of v8
# speedup vs baseline: 1.0538x; 1.0021x over previous
; __device__ __forceinline__ unsigned cvt_pk_bf16(float lo, float hi) { unsigned r; asm volatile("v_cvt_pk_bf16_f32 %0, %1, %2" : "=v"(r) : "v"(lo), "v"(hi)); return r; }
;     __device__ __forceinline__ void operator()(const f32x4 (&acc)[2][2][4][2], const Unit& u, int wr, int wc, int fr, int fq) const {
;         const int col = u.pn * 128 + wc * 32 + 8 * fq; const int row0 = u.pm * 256 + wr * 64 + fr;
;         float rsv[8];
; #pragma unroll
;         for (int i = 0; i < 8; ++i) rsv[i] = ssq[row0 + (i >> 2) * 128 + (i & 3) * 16];
; #pragma unroll
;         for (int ai = 0; ai < 2; ++ai)
; #pragma unroll
;             for (int m = 0; m < 4; ++m) { const int row = row0 + ai * 128 + m * 16; const float rs = rsqrtf(rsv[ai * 4 + m] * (1.f / D) + EPS); float h[8];
; #pragma unroll
;                 for (int j = 0; j < 8; ++j) { const float gv = acc[ai][0][m][j >> 2][j & 3] * rs, uv = acc[ai][1][m][j >> 2][j & 3] * rs; h[j] = gv / (1.f + __expf(-gv)) * uv; }
;                 u32x4 w; w.x = cvt_pk_bf16(h[0], h[1]); w.y = cvt_pk_bf16(h[2], h[3]); w.z = cvt_pk_bf16(h[4], h[5]); w.w = cvt_pk_bf16(h[6], h[7]);
;                 *(u32x4*)(H + (size_t)row * FF + col) = w; }
.LBB0_950:
	s_lshl_b32 s100, s8, 8
	s_mul_i32 s101, s100, 0x1600
	s_lshl_b32 s100, s9, 8
	s_add_i32 s101, s101, s100
	s_add_u32 s98, s96, s101
	s_addc_u32 s99, s97, 0
	v_lshlrev_b32_e32 v250, 1, v150
	v_mad_u32_u24 v250, v148, s52, v250
	s_and_b64 s[100:101], s[6:7], exec
	s_cselect_b32 s100, s8, s28
	v_lshl_add_u32 v255, s100, 8, v148
	v_lshlrev_b32_e32 v255, 2, v255
	v_fmamk_f32 v254, v242, 0x3a800000, v154
	v_rsq_f32_e32 v252, v254
	global_load_dword v242, v255, s[90:91] offset:0
	v_pk_mul_f32 v[124:125], v[120:121], v[124:125]
	v_pk_mul_f32 v[126:127], v[122:123], v[126:127]
	v_pk_mul_f32 v[116:117], v[112:113], v[116:117]
	v_pk_mul_f32 v[118:119], v[114:115], v[118:119]
	v_mul_f32_e32 v252, 0xbfb8aa3b, v252
	v_pk_mul_f32 v[120:121], v[120:121], v[252:253] op_sel_hi:[1,0]
	v_pk_mul_f32 v[122:123], v[122:123], v[252:253] op_sel_hi:[1,0]
	v_pk_mul_f32 v[112:113], v[112:113], v[252:253] op_sel_hi:[1,0]
	v_pk_mul_f32 v[114:115], v[114:115], v[252:253] op_sel_hi:[1,0]
	v_exp_f32_e32 v120, v120
	v_exp_f32_e32 v121, v121
	v_exp_f32_e32 v122, v122
	v_exp_f32_e32 v123, v123
	v_exp_f32_e32 v112, v112
	v_exp_f32_e32 v113, v113
	v_exp_f32_e32 v114, v114
	v_exp_f32_e32 v115, v115
	v_pk_fma_f32 v[120:121], v[120:121], v[254:255], v[254:255] op_sel_hi:[1,0,0]
	v_pk_fma_f32 v[122:123], v[122:123], v[254:255], v[254:255] op_sel_hi:[1,0,0]
	v_pk_fma_f32 v[112:113], v[112:113], v[254:255], v[254:255] op_sel_hi:[1,0,0]
	v_pk_fma_f32 v[114:115], v[114:115], v[254:255], v[254:255] op_sel_hi:[1,0,0]
	v_rcp_f32_e32 v120, v120
	v_rcp_f32_e32 v121, v121
	v_rcp_f32_e32 v122, v122
	v_rcp_f32_e32 v123, v123
	v_rcp_f32_e32 v112, v112
	v_rcp_f32_e32 v113, v113
	v_rcp_f32_e32 v114, v114
	v_rcp_f32_e32 v115, v115
	v_pk_mul_f32 v[124:125], v[124:125], v[120:121]
	v_pk_mul_f32 v[126:127], v[126:127], v[122:123]
	v_pk_mul_f32 v[116:117], v[116:117], v[112:113]
	v_pk_mul_f32 v[118:119], v[118:119], v[114:115]
	v_cvt_pk_bf16_f32 v120, v124, v125
	v_cvt_pk_bf16_f32 v121, v126, v127
	v_cvt_pk_bf16_f32 v122, v116, v117
	v_cvt_pk_bf16_f32 v123, v118, v119
	global_store_dwordx4 v250, v[120:123], s[98:99]
	v_fmamk_f32 v254, v243, 0x3a800000, v154
	v_rsq_f32_e32 v252, v254
	global_load_dword v243, v255, s[90:91] offset:64
	v_pk_mul_f32 v[108:109], v[104:105], v[108:109]
	v_pk_mul_f32 v[110:111], v[106:107], v[110:111]
	v_pk_mul_f32 v[100:101], v[96:97], v[100:101]
	v_pk_mul_f32 v[102:103], v[98:99], v[102:103]
	v_mul_f32_e32 v252, 0xbfb8aa3b, v252
	v_pk_mul_f32 v[104:105], v[104:105], v[252:253] op_sel_hi:[1,0]
	v_pk_mul_f32 v[106:107], v[106:107], v[252:253] op_sel_hi:[1,0]
	v_pk_mul_f32 v[96:97], v[96:97], v[252:253] op_sel_hi:[1,0]
	v_pk_mul_f32 v[98:99], v[98:99], v[252:253] op_sel_hi:[1,0]
	v_exp_f32_e32 v104, v104
	v_exp_f32_e32 v105, v105
	v_exp_f32_e32 v106, v106
	v_exp_f32_e32 v107, v107
	v_exp_f32_e32 v96, v96
	v_exp_f32_e32 v97, v97
	v_exp_f32_e32 v98, v98
	v_exp_f32_e32 v99, v99
	v_pk_fma_f32 v[104:105], v[104:105], v[254:255], v[254:255] op_sel_hi:[1,0,0]
	v_pk_fma_f32 v[106:107], v[106:107], v[254:255], v[254:255] op_sel_hi:[1,0,0]
	v_pk_fma_f32 v[96:97], v[96:97], v[254:255], v[254:255] op_sel_hi:[1,0,0]
	v_pk_fma_f32 v[98:99], v[98:99], v[254:255], v[254:255] op_sel_hi:[1,0,0]
	v_rcp_f32_e32 v104, v104
	v_rcp_f32_e32 v105, v105
	v_rcp_f32_e32 v106, v106
	v_rcp_f32_e32 v107, v107
	v_rcp_f32_e32 v96, v96
	v_rcp_f32_e32 v97, v97
	v_rcp_f32_e32 v98, v98
	v_rcp_f32_e32 v99, v99
	v_pk_mul_f32 v[108:109], v[108:109], v[104:105]
	v_pk_mul_f32 v[110:111], v[110:111], v[106:107]
	v_pk_mul_f32 v[100:101], v[100:101], v[96:97]
	v_pk_mul_f32 v[102:103], v[102:103], v[98:99]
	v_cvt_pk_bf16_f32 v104, v108, v109
	v_cvt_pk_bf16_f32 v105, v110, v111
	v_cvt_pk_bf16_f32 v106, v100, v101
	v_cvt_pk_bf16_f32 v107, v102, v103
	s_add_u32 s98, s98, 0x16000
	s_addc_u32 s99, s99, 0
	global_store_dwordx4 v250, v[104:107], s[98:99]
	v_fmamk_f32 v254, v244, 0x3a800000, v154
	v_rsq_f32_e32 v252, v254
	global_load_dword v244, v255, s[90:91] offset:128
	v_pk_mul_f32 v[92:93], v[88:89], v[92:93]
	v_pk_mul_f32 v[94:95], v[90:91], v[94:95]
	v_pk_mul_f32 v[84:85], v[80:81], v[84:85]
	v_pk_mul_f32 v[86:87], v[82:83], v[86:87]
	v_mul_f32_e32 v252, 0xbfb8aa3b, v252
	v_pk_mul_f32 v[88:89], v[88:89], v[252:253] op_sel_hi:[1,0]
	v_pk_mul_f32 v[90:91], v[90:91], v[252:253] op_sel_hi:[1,0]
	v_pk_mul_f32 v[80:81], v[80:81], v[252:253] op_sel_hi:[1,0]
	v_pk_mul_f32 v[82:83], v[82:83], v[252:253] op_sel_hi:[1,0]
	v_exp_f32_e32 v88, v88
	v_exp_f32_e32 v89, v89
	v_exp_f32_e32 v90, v90
	v_exp_f32_e32 v91, v91
	v_exp_f32_e32 v80, v80
	v_exp_f32_e32 v81, v81
	v_exp_f32_e32 v82, v82
	v_exp_f32_e32 v83, v83
	v_pk_fma_f32 v[88:89], v[88:89], v[254:255], v[254:255] op_sel_hi:[1,0,0]
	v_pk_fma_f32 v[90:91], v[90:91], v[254:255], v[254:255] op_sel_hi:[1,0,0]
	v_pk_fma_f32 v[80:81], v[80:81], v[254:255], v[254:255] op_sel_hi:[1,0,0]
	v_pk_fma_f32 v[82:83], v[82:83], v[254:255], v[254:255] op_sel_hi:[1,0,0]
	v_rcp_f32_e32 v88, v88
	v_rcp_f32_e32 v89, v89
	v_rcp_f32_e32 v90, v90
	v_rcp_f32_e32 v91, v91
	v_rcp_f32_e32 v80, v80
	v_rcp_f32_e32 v81, v81
	v_rcp_f32_e32 v82, v82
	v_rcp_f32_e32 v83, v83
	v_pk_mul_f32 v[92:93], v[92:93], v[88:89]
	v_pk_mul_f32 v[94:95], v[94:95], v[90:91]
	v_pk_mul_f32 v[84:85], v[84:85], v[80:81]
	v_pk_mul_f32 v[86:87], v[86:87], v[82:83]
	v_cvt_pk_bf16_f32 v88, v92, v93
	v_cvt_pk_bf16_f32 v89, v94, v95
	v_cvt_pk_bf16_f32 v90, v84, v85
	v_cvt_pk_bf16_f32 v91, v86, v87
	s_add_u32 s98, s98, 0x16000
	s_addc_u32 s99, s99, 0
	global_store_dwordx4 v250, v[88:91], s[98:99]
	v_fmamk_f32 v254, v245, 0x3a800000, v154
	v_rsq_f32_e32 v252, v254
	global_load_dword v245, v255, s[90:91] offset:192
; __device__ __forceinline__ unsigned cvt_pk_bf16(float lo, float hi) { unsigned r; asm volatile("v_cvt_pk_bf16_f32 %0, %1, %2" : "=v"(r) : "v"(lo), "v"(hi)); return r; }
;     __device__ __forceinline__ void operator()(const f32x4 (&acc)[2][2][4][2], const Unit& u, int wr, int wc, int fr, int fq) const {
;         const int col = u.pn * 128 + wc * 32 + 8 * fq; const int row0 = u.pm * 256 + wr * 64 + fr;
;         float rsv[8];
; #pragma unroll
;         for (int i = 0; i < 8; ++i) rsv[i] = ssq[row0 + (i >> 2) * 128 + (i & 3) * 16];
; #pragma unroll
;         for (int ai = 0; ai < 2; ++ai)
; #pragma unroll
;             for (int m = 0; m < 4; ++m) { const int row = row0 + ai * 128 + m * 16; const float rs = rsqrtf(rsv[ai * 4 + m] * (1.f / D) + EPS); float h[8];
; #pragma unroll
;                 for (int j = 0; j < 8; ++j) { const float gv = acc[ai][0][m][j >> 2][j & 3] * rs, uv = acc[ai][1][m][j >> 2][j & 3] * rs; h[j] = gv / (1.f + __expf(-gv)) * uv; }
;                 u32x4 w; w.x = cvt_pk_bf16(h[0], h[1]); w.y = cvt_pk_bf16(h[2], h[3]); w.z = cvt_pk_bf16(h[4], h[5]); w.w = cvt_pk_bf16(h[6], h[7]);
;                 *(u32x4*)(H + (size_t)row * FF + col) = w; }
	v_pk_mul_f32 v[76:77], v[72:73], v[76:77]
	v_pk_mul_f32 v[78:79], v[74:75], v[78:79]
	v_pk_mul_f32 v[68:69], v[64:65], v[68:69]
	v_pk_mul_f32 v[70:71], v[66:67], v[70:71]
	v_mul_f32_e32 v252, 0xbfb8aa3b, v252
	v_pk_mul_f32 v[72:73], v[72:73], v[252:253] op_sel_hi:[1,0]
	v_pk_mul_f32 v[74:75], v[74:75], v[252:253] op_sel_hi:[1,0]
	v_pk_mul_f32 v[64:65], v[64:65], v[252:253] op_sel_hi:[1,0]
	v_pk_mul_f32 v[66:67], v[66:67], v[252:253] op_sel_hi:[1,0]
	v_exp_f32_e32 v72, v72
	v_exp_f32_e32 v73, v73
	v_exp_f32_e32 v74, v74
	v_exp_f32_e32 v75, v75
	v_exp_f32_e32 v64, v64
	v_exp_f32_e32 v65, v65
	v_exp_f32_e32 v66, v66
	v_exp_f32_e32 v67, v67
	v_pk_fma_f32 v[72:73], v[72:73], v[254:255], v[254:255] op_sel_hi:[1,0,0]
	v_pk_fma_f32 v[74:75], v[74:75], v[254:255], v[254:255] op_sel_hi:[1,0,0]
	v_pk_fma_f32 v[64:65], v[64:65], v[254:255], v[254:255] op_sel_hi:[1,0,0]
	v_pk_fma_f32 v[66:67], v[66:67], v[254:255], v[254:255] op_sel_hi:[1,0,0]
	v_rcp_f32_e32 v72, v72
	v_rcp_f32_e32 v73, v73
	v_rcp_f32_e32 v74, v74
	v_rcp_f32_e32 v75, v75
	v_rcp_f32_e32 v64, v64
	v_rcp_f32_e32 v65, v65
	v_rcp_f32_e32 v66, v66
	v_rcp_f32_e32 v67, v67
	v_pk_mul_f32 v[76:77], v[76:77], v[72:73]
	v_pk_mul_f32 v[78:79], v[78:79], v[74:75]
	v_pk_mul_f32 v[68:69], v[68:69], v[64:65]
	v_pk_mul_f32 v[70:71], v[70:71], v[66:67]
	v_cvt_pk_bf16_f32 v72, v76, v77
	v_cvt_pk_bf16_f32 v73, v78, v79
	v_cvt_pk_bf16_f32 v74, v68, v69
	v_cvt_pk_bf16_f32 v75, v70, v71
	s_add_u32 s98, s98, 0x16000
	s_addc_u32 s99, s99, 0
	global_store_dwordx4 v250, v[72:75], s[98:99]
	v_fmamk_f32 v254, v246, 0x3a800000, v154
	v_rsq_f32_e32 v252, v254
	global_load_dword v246, v255, s[90:91] offset:512
	v_pk_mul_f32 v[60:61], v[56:57], v[60:61]
	v_pk_mul_f32 v[62:63], v[58:59], v[62:63]
	v_pk_mul_f32 v[52:53], v[48:49], v[52:53]
	v_pk_mul_f32 v[54:55], v[50:51], v[54:55]
	v_mul_f32_e32 v252, 0xbfb8aa3b, v252
	v_pk_mul_f32 v[56:57], v[56:57], v[252:253] op_sel_hi:[1,0]
	v_pk_mul_f32 v[58:59], v[58:59], v[252:253] op_sel_hi:[1,0]
	v_pk_mul_f32 v[48:49], v[48:49], v[252:253] op_sel_hi:[1,0]
	v_pk_mul_f32 v[50:51], v[50:51], v[252:253] op_sel_hi:[1,0]
	v_exp_f32_e32 v56, v56
	v_exp_f32_e32 v57, v57
	v_exp_f32_e32 v58, v58
	v_exp_f32_e32 v59, v59
	v_exp_f32_e32 v48, v48
	v_exp_f32_e32 v49, v49
	v_exp_f32_e32 v50, v50
	v_exp_f32_e32 v51, v51
	v_pk_fma_f32 v[56:57], v[56:57], v[254:255], v[254:255] op_sel_hi:[1,0,0]
	v_pk_fma_f32 v[58:59], v[58:59], v[254:255], v[254:255] op_sel_hi:[1,0,0]
	v_pk_fma_f32 v[48:49], v[48:49], v[254:255], v[254:255] op_sel_hi:[1,0,0]
	v_pk_fma_f32 v[50:51], v[50:51], v[254:255], v[254:255] op_sel_hi:[1,0,0]
	v_rcp_f32_e32 v56, v56
	v_rcp_f32_e32 v57, v57
	v_rcp_f32_e32 v58, v58
	v_rcp_f32_e32 v59, v59
	v_rcp_f32_e32 v48, v48
	v_rcp_f32_e32 v49, v49
	v_rcp_f32_e32 v50, v50
	v_rcp_f32_e32 v51, v51
	v_pk_mul_f32 v[60:61], v[60:61], v[56:57]
	v_pk_mul_f32 v[62:63], v[62:63], v[58:59]
	v_pk_mul_f32 v[52:53], v[52:53], v[48:49]
	v_pk_mul_f32 v[54:55], v[54:55], v[50:51]
	v_cvt_pk_bf16_f32 v56, v60, v61
	v_cvt_pk_bf16_f32 v57, v62, v63
	v_cvt_pk_bf16_f32 v58, v52, v53
	v_cvt_pk_bf16_f32 v59, v54, v55
	s_add_u32 s98, s98, 0x6e000
	s_addc_u32 s99, s99, 0
	global_store_dwordx4 v250, v[56:59], s[98:99]
	v_fmamk_f32 v254, v247, 0x3a800000, v154
	v_rsq_f32_e32 v252, v254
	global_load_dword v247, v255, s[90:91] offset:576
	v_pk_mul_f32 v[44:45], v[40:41], v[44:45]
	v_pk_mul_f32 v[46:47], v[42:43], v[46:47]
	v_pk_mul_f32 v[36:37], v[32:33], v[36:37]
	v_pk_mul_f32 v[38:39], v[34:35], v[38:39]
	v_mul_f32_e32 v252, 0xbfb8aa3b, v252
	v_pk_mul_f32 v[40:41], v[40:41], v[252:253] op_sel_hi:[1,0]
	v_pk_mul_f32 v[42:43], v[42:43], v[252:253] op_sel_hi:[1,0]
	v_pk_mul_f32 v[32:33], v[32:33], v[252:253] op_sel_hi:[1,0]
	v_pk_mul_f32 v[34:35], v[34:35], v[252:253] op_sel_hi:[1,0]
	v_exp_f32_e32 v40, v40
	v_exp_f32_e32 v41, v41
	v_exp_f32_e32 v42, v42
	v_exp_f32_e32 v43, v43
	v_exp_f32_e32 v32, v32
	v_exp_f32_e32 v33, v33
	v_exp_f32_e32 v34, v34
	v_exp_f32_e32 v35, v35
	v_pk_fma_f32 v[40:41], v[40:41], v[254:255], v[254:255] op_sel_hi:[1,0,0]
	v_pk_fma_f32 v[42:43], v[42:43], v[254:255], v[254:255] op_sel_hi:[1,0,0]
; __device__ __forceinline__ unsigned cvt_pk_bf16(float lo, float hi) { unsigned r; asm volatile("v_cvt_pk_bf16_f32 %0, %1, %2" : "=v"(r) : "v"(lo), "v"(hi)); return r; }
;     __device__ __forceinline__ void operator()(const f32x4 (&acc)[2][2][4][2], const Unit& u, int wr, int wc, int fr, int fq) const {
;         const int col = u.pn * 128 + wc * 32 + 8 * fq; const int row0 = u.pm * 256 + wr * 64 + fr;
;         float rsv[8];
; #pragma unroll
;         for (int i = 0; i < 8; ++i) rsv[i] = ssq[row0 + (i >> 2) * 128 + (i & 3) * 16];
; #pragma unroll
;         for (int ai = 0; ai < 2; ++ai)
; #pragma unroll
;             for (int m = 0; m < 4; ++m) { const int row = row0 + ai * 128 + m * 16; const float rs = rsqrtf(rsv[ai * 4 + m] * (1.f / D) + EPS); float h[8];
; #pragma unroll
;                 for (int j = 0; j < 8; ++j) { const float gv = acc[ai][0][m][j >> 2][j & 3] * rs, uv = acc[ai][1][m][j >> 2][j & 3] * rs; h[j] = gv / (1.f + __expf(-gv)) * uv; }
;                 u32x4 w; w.x = cvt_pk_bf16(h[0], h[1]); w.y = cvt_pk_bf16(h[2], h[3]); w.z = cvt_pk_bf16(h[4], h[5]); w.w = cvt_pk_bf16(h[6], h[7]);
;                 *(u32x4*)(H + (size_t)row * FF + col) = w; }
	v_pk_fma_f32 v[32:33], v[32:33], v[254:255], v[254:255] op_sel_hi:[1,0,0]
	v_pk_fma_f32 v[34:35], v[34:35], v[254:255], v[254:255] op_sel_hi:[1,0,0]
	v_rcp_f32_e32 v40, v40
	v_rcp_f32_e32 v41, v41
	v_rcp_f32_e32 v42, v42
	v_rcp_f32_e32 v43, v43
	v_rcp_f32_e32 v32, v32
	v_rcp_f32_e32 v33, v33
	v_rcp_f32_e32 v34, v34
	v_rcp_f32_e32 v35, v35
	v_pk_mul_f32 v[44:45], v[44:45], v[40:41]
	v_pk_mul_f32 v[46:47], v[46:47], v[42:43]
	v_pk_mul_f32 v[36:37], v[36:37], v[32:33]
	v_pk_mul_f32 v[38:39], v[38:39], v[34:35]
	v_cvt_pk_bf16_f32 v40, v44, v45
	v_cvt_pk_bf16_f32 v41, v46, v47
	v_cvt_pk_bf16_f32 v42, v36, v37
	v_cvt_pk_bf16_f32 v43, v38, v39
	s_add_u32 s98, s98, 0x16000
	s_addc_u32 s99, s99, 0
	global_store_dwordx4 v250, v[40:43], s[98:99]
	v_fmamk_f32 v254, v248, 0x3a800000, v154
	v_rsq_f32_e32 v252, v254
	global_load_dword v248, v255, s[90:91] offset:640
	v_pk_mul_f32 v[28:29], v[24:25], v[28:29]
	v_pk_mul_f32 v[30:31], v[26:27], v[30:31]
	v_pk_mul_f32 v[20:21], v[16:17], v[20:21]
	v_pk_mul_f32 v[22:23], v[18:19], v[22:23]
	v_mul_f32_e32 v252, 0xbfb8aa3b, v252
	v_pk_mul_f32 v[24:25], v[24:25], v[252:253] op_sel_hi:[1,0]
	v_pk_mul_f32 v[26:27], v[26:27], v[252:253] op_sel_hi:[1,0]
	v_pk_mul_f32 v[16:17], v[16:17], v[252:253] op_sel_hi:[1,0]
	v_pk_mul_f32 v[18:19], v[18:19], v[252:253] op_sel_hi:[1,0]
	v_exp_f32_e32 v24, v24
	v_exp_f32_e32 v25, v25
	v_exp_f32_e32 v26, v26
	v_exp_f32_e32 v27, v27
	v_exp_f32_e32 v16, v16
	v_exp_f32_e32 v17, v17
	v_exp_f32_e32 v18, v18
	v_exp_f32_e32 v19, v19
	v_pk_fma_f32 v[24:25], v[24:25], v[254:255], v[254:255] op_sel_hi:[1,0,0]
	v_pk_fma_f32 v[26:27], v[26:27], v[254:255], v[254:255] op_sel_hi:[1,0,0]
	v_pk_fma_f32 v[16:17], v[16:17], v[254:255], v[254:255] op_sel_hi:[1,0,0]
	v_pk_fma_f32 v[18:19], v[18:19], v[254:255], v[254:255] op_sel_hi:[1,0,0]
	v_rcp_f32_e32 v24, v24
	v_rcp_f32_e32 v25, v25
	v_rcp_f32_e32 v26, v26
	v_rcp_f32_e32 v27, v27
	v_rcp_f32_e32 v16, v16
	v_rcp_f32_e32 v17, v17
	v_rcp_f32_e32 v18, v18
	v_rcp_f32_e32 v19, v19
	v_pk_mul_f32 v[28:29], v[28:29], v[24:25]
	v_pk_mul_f32 v[30:31], v[30:31], v[26:27]
	v_pk_mul_f32 v[20:21], v[20:21], v[16:17]
	v_pk_mul_f32 v[22:23], v[22:23], v[18:19]
	v_cvt_pk_bf16_f32 v24, v28, v29
	v_cvt_pk_bf16_f32 v25, v30, v31
	v_cvt_pk_bf16_f32 v26, v20, v21
	v_cvt_pk_bf16_f32 v27, v22, v23
	s_add_u32 s98, s98, 0x16000
	s_addc_u32 s99, s99, 0
	global_store_dwordx4 v250, v[24:27], s[98:99]
	v_fmamk_f32 v254, v249, 0x3a800000, v154
	v_rsq_f32_e32 v252, v254
	global_load_dword v249, v255, s[90:91] offset:704
	v_pk_mul_f32 v[12:13], v[8:9], v[12:13]
	v_pk_mul_f32 v[14:15], v[10:11], v[14:15]
	v_pk_mul_f32 v[0:1], v[4:5], v[0:1]
	v_pk_mul_f32 v[2:3], v[6:7], v[2:3]
	v_mul_f32_e32 v252, 0xbfb8aa3b, v252
	v_pk_mul_f32 v[8:9], v[8:9], v[252:253] op_sel_hi:[1,0]
	v_pk_mul_f32 v[10:11], v[10:11], v[252:253] op_sel_hi:[1,0]
	v_pk_mul_f32 v[4:5], v[4:5], v[252:253] op_sel_hi:[1,0]
	v_pk_mul_f32 v[6:7], v[6:7], v[252:253] op_sel_hi:[1,0]
	v_exp_f32_e32 v8, v8
	v_exp_f32_e32 v9, v9
	v_exp_f32_e32 v10, v10
	v_exp_f32_e32 v11, v11
	v_exp_f32_e32 v4, v4
	v_exp_f32_e32 v5, v5
	v_exp_f32_e32 v6, v6
	v_exp_f32_e32 v7, v7
	v_pk_fma_f32 v[8:9], v[8:9], v[254:255], v[254:255] op_sel_hi:[1,0,0]
	v_pk_fma_f32 v[10:11], v[10:11], v[254:255], v[254:255] op_sel_hi:[1,0,0]
	v_pk_fma_f32 v[4:5], v[4:5], v[254:255], v[254:255] op_sel_hi:[1,0,0]
	v_pk_fma_f32 v[6:7], v[6:7], v[254:255], v[254:255] op_sel_hi:[1,0,0]
	v_rcp_f32_e32 v8, v8
	v_rcp_f32_e32 v9, v9
	v_rcp_f32_e32 v10, v10
	v_rcp_f32_e32 v11, v11
	v_rcp_f32_e32 v4, v4
	v_rcp_f32_e32 v5, v5
	v_rcp_f32_e32 v6, v6
	v_rcp_f32_e32 v7, v7
	v_pk_mul_f32 v[12:13], v[12:13], v[8:9]
	v_pk_mul_f32 v[14:15], v[14:15], v[10:11]
	v_pk_mul_f32 v[0:1], v[0:1], v[4:5]
	v_pk_mul_f32 v[2:3], v[2:3], v[6:7]
	v_cvt_pk_bf16_f32 v8, v12, v13
	v_cvt_pk_bf16_f32 v9, v14, v15
	v_cvt_pk_bf16_f32 v10, v0, v1
	v_cvt_pk_bf16_f32 v11, v2, v3
	s_add_u32 s98, s98, 0x16000
	s_addc_u32 s99, s99, 0
	global_store_dwordx4 v250, v[8:11], s[98:99]
	s_and_b64 vcc, exec, s[6:7]
	s_mov_b64 s[0:1], -1
	s_cbranch_vccnz .LBB0_940
	s_andn2_b64 vcc, exec, s[18:19]
	s_cbranch_vccnz .LBB0_939
	s_barrier
	s_branch .LBB0_939

; __device__ __forceinline__ unsigned cvt_pk_bf16(float lo, float hi) { unsigned r; asm volatile("v_cvt_pk_bf16_f32 %0, %1, %2" : "=v"(r) : "v"(lo), "v"(hi)); return r; }
;     __device__ __forceinline__ void operator()(const f32x4 (&acc)[2][2][4][2], const Unit& u, int wr, int wc, int fr, int fq) const {
;         const int col = u.pn * 128 + wc * 32 + 8 * fq; const int row0 = u.pm * 256 + wr * 64 + fr;
;         float rsv[8];
; #pragma unroll
;         for (int i = 0; i < 8; ++i) rsv[i] = ssq[row0 + (i >> 2) * 128 + (i & 3) * 16];
; #pragma unroll
;         for (int ai = 0; ai < 2; ++ai)
; #pragma unroll
;             for (int m = 0; m < 4; ++m) { const int row = row0 + ai * 128 + m * 16; const float rs = rsqrtf(rsv[ai * 4 + m] * (1.f / D) + EPS); float h[8];
; #pragma unroll
;                 for (int j = 0; j < 8; ++j) { const float gv = acc[ai][0][m][j >> 2][j & 3] * rs, uv = acc[ai][1][m][j >> 2][j & 3] * rs; h[j] = gv / (1.f + __expf(-gv)) * uv; }
;                 u32x4 w; w.x = cvt_pk_bf16(h[0], h[1]); w.y = cvt_pk_bf16(h[2], h[3]); w.z = cvt_pk_bf16(h[4], h[5]); w.w = cvt_pk_bf16(h[6], h[7]);
;                 *(u32x4*)(H + (size_t)row * FF + col) = w; }
.LBB0_1604:
	s_lshl_b32 s100, s8, 8
	s_mul_i32 s101, s100, 0x1600
	s_lshl_b32 s100, s9, 8
	s_add_i32 s101, s101, s100
	s_add_u32 s98, s96, s101
	s_addc_u32 s99, s97, 0
	v_lshlrev_b32_e32 v250, 1, v151
	v_mad_u32_u24 v250, v131, s52, v250
	s_and_b64 s[100:101], s[6:7], exec
	s_cselect_b32 s100, s8, s28
	v_lshl_add_u32 v255, s100, 8, v131
	v_lshlrev_b32_e32 v255, 2, v255
	v_fmamk_f32 v254, v242, 0x3a800000, v155
	v_rsq_f32_e32 v252, v254
	global_load_dword v242, v255, s[14:15] offset:0
	v_pk_mul_f32 v[124:125], v[120:121], v[124:125]
	v_pk_mul_f32 v[126:127], v[122:123], v[126:127]
	v_pk_mul_f32 v[116:117], v[112:113], v[116:117]
	v_pk_mul_f32 v[118:119], v[114:115], v[118:119]
	v_mul_f32_e32 v252, 0xbfb8aa3b, v252
	v_pk_mul_f32 v[120:121], v[120:121], v[252:253] op_sel_hi:[1,0]
	v_pk_mul_f32 v[122:123], v[122:123], v[252:253] op_sel_hi:[1,0]
	v_pk_mul_f32 v[112:113], v[112:113], v[252:253] op_sel_hi:[1,0]
	v_pk_mul_f32 v[114:115], v[114:115], v[252:253] op_sel_hi:[1,0]
	v_exp_f32_e32 v120, v120
	v_exp_f32_e32 v121, v121
	v_exp_f32_e32 v122, v122
	v_exp_f32_e32 v123, v123
	v_exp_f32_e32 v112, v112
	v_exp_f32_e32 v113, v113
	v_exp_f32_e32 v114, v114
	v_exp_f32_e32 v115, v115
	v_pk_fma_f32 v[120:121], v[120:121], v[254:255], v[254:255] op_sel_hi:[1,0,0]
	v_pk_fma_f32 v[122:123], v[122:123], v[254:255], v[254:255] op_sel_hi:[1,0,0]
	v_pk_fma_f32 v[112:113], v[112:113], v[254:255], v[254:255] op_sel_hi:[1,0,0]
	v_pk_fma_f32 v[114:115], v[114:115], v[254:255], v[254:255] op_sel_hi:[1,0,0]
	v_rcp_f32_e32 v120, v120
	v_rcp_f32_e32 v121, v121
	v_rcp_f32_e32 v122, v122
	v_rcp_f32_e32 v123, v123
	v_rcp_f32_e32 v112, v112
	v_rcp_f32_e32 v113, v113
	v_rcp_f32_e32 v114, v114
	v_rcp_f32_e32 v115, v115
	v_pk_mul_f32 v[124:125], v[124:125], v[120:121]
	v_pk_mul_f32 v[126:127], v[126:127], v[122:123]
	v_pk_mul_f32 v[116:117], v[116:117], v[112:113]
	v_pk_mul_f32 v[118:119], v[118:119], v[114:115]
	v_cvt_pk_bf16_f32 v120, v124, v125
	v_cvt_pk_bf16_f32 v121, v126, v127
	v_cvt_pk_bf16_f32 v122, v116, v117
	v_cvt_pk_bf16_f32 v123, v118, v119
	global_store_dwordx4 v250, v[120:123], s[98:99]
	v_fmamk_f32 v254, v243, 0x3a800000, v155
	v_rsq_f32_e32 v252, v254
	global_load_dword v243, v255, s[14:15] offset:64
	v_pk_mul_f32 v[108:109], v[104:105], v[108:109]
	v_pk_mul_f32 v[110:111], v[106:107], v[110:111]
	v_pk_mul_f32 v[100:101], v[96:97], v[100:101]
	v_pk_mul_f32 v[102:103], v[98:99], v[102:103]
	v_mul_f32_e32 v252, 0xbfb8aa3b, v252
	v_pk_mul_f32 v[104:105], v[104:105], v[252:253] op_sel_hi:[1,0]
	v_pk_mul_f32 v[106:107], v[106:107], v[252:253] op_sel_hi:[1,0]
	v_pk_mul_f32 v[96:97], v[96:97], v[252:253] op_sel_hi:[1,0]
	v_pk_mul_f32 v[98:99], v[98:99], v[252:253] op_sel_hi:[1,0]
	v_exp_f32_e32 v104, v104
	v_exp_f32_e32 v105, v105
	v_exp_f32_e32 v106, v106
	v_exp_f32_e32 v107, v107
	v_exp_f32_e32 v96, v96
	v_exp_f32_e32 v97, v97
	v_exp_f32_e32 v98, v98
	v_exp_f32_e32 v99, v99
	v_pk_fma_f32 v[104:105], v[104:105], v[254:255], v[254:255] op_sel_hi:[1,0,0]
	v_pk_fma_f32 v[106:107], v[106:107], v[254:255], v[254:255] op_sel_hi:[1,0,0]
	v_pk_fma_f32 v[96:97], v[96:97], v[254:255], v[254:255] op_sel_hi:[1,0,0]
	v_pk_fma_f32 v[98:99], v[98:99], v[254:255], v[254:255] op_sel_hi:[1,0,0]
	v_rcp_f32_e32 v104, v104
	v_rcp_f32_e32 v105, v105
	v_rcp_f32_e32 v106, v106
	v_rcp_f32_e32 v107, v107
	v_rcp_f32_e32 v96, v96
	v_rcp_f32_e32 v97, v97
	v_rcp_f32_e32 v98, v98
	v_rcp_f32_e32 v99, v99
	v_pk_mul_f32 v[108:109], v[108:109], v[104:105]
	v_pk_mul_f32 v[110:111], v[110:111], v[106:107]
	v_pk_mul_f32 v[100:101], v[100:101], v[96:97]
	v_pk_mul_f32 v[102:103], v[102:103], v[98:99]
	v_cvt_pk_bf16_f32 v104, v108, v109
	v_cvt_pk_bf16_f32 v105, v110, v111
	v_cvt_pk_bf16_f32 v106, v100, v101
	v_cvt_pk_bf16_f32 v107, v102, v103
	s_add_u32 s98, s98, 0x16000
	s_addc_u32 s99, s99, 0
	global_store_dwordx4 v250, v[104:107], s[98:99]
	v_fmamk_f32 v254, v244, 0x3a800000, v155
	v_rsq_f32_e32 v252, v254
	global_load_dword v244, v255, s[14:15] offset:128
	v_pk_mul_f32 v[92:93], v[88:89], v[92:93]
	v_pk_mul_f32 v[94:95], v[90:91], v[94:95]
	v_pk_mul_f32 v[84:85], v[80:81], v[84:85]
	v_pk_mul_f32 v[86:87], v[82:83], v[86:87]
	v_mul_f32_e32 v252, 0xbfb8aa3b, v252
	v_pk_mul_f32 v[88:89], v[88:89], v[252:253] op_sel_hi:[1,0]
	v_pk_mul_f32 v[90:91], v[90:91], v[252:253] op_sel_hi:[1,0]
	v_pk_mul_f32 v[80:81], v[80:81], v[252:253] op_sel_hi:[1,0]
	v_pk_mul_f32 v[82:83], v[82:83], v[252:253] op_sel_hi:[1,0]
	v_exp_f32_e32 v88, v88
	v_exp_f32_e32 v89, v89
	v_exp_f32_e32 v90, v90
	v_exp_f32_e32 v91, v91
	v_exp_f32_e32 v80, v80
	v_exp_f32_e32 v81, v81
	v_exp_f32_e32 v82, v82
	v_exp_f32_e32 v83, v83
	v_pk_fma_f32 v[88:89], v[88:89], v[254:255], v[254:255] op_sel_hi:[1,0,0]
	v_pk_fma_f32 v[90:91], v[90:91], v[254:255], v[254:255] op_sel_hi:[1,0,0]
	v_pk_fma_f32 v[80:81], v[80:81], v[254:255], v[254:255] op_sel_hi:[1,0,0]
	v_pk_fma_f32 v[82:83], v[82:83], v[254:255], v[254:255] op_sel_hi:[1,0,0]
	v_rcp_f32_e32 v88, v88
	v_rcp_f32_e32 v89, v89
	v_rcp_f32_e32 v90, v90
	v_rcp_f32_e32 v91, v91
	v_rcp_f32_e32 v80, v80
	v_rcp_f32_e32 v81, v81
	v_rcp_f32_e32 v82, v82
	v_rcp_f32_e32 v83, v83
	v_pk_mul_f32 v[92:93], v[92:93], v[88:89]
	v_pk_mul_f32 v[94:95], v[94:95], v[90:91]
	v_pk_mul_f32 v[84:85], v[84:85], v[80:81]
	v_pk_mul_f32 v[86:87], v[86:87], v[82:83]
	v_cvt_pk_bf16_f32 v88, v92, v93
	v_cvt_pk_bf16_f32 v89, v94, v95
	v_cvt_pk_bf16_f32 v90, v84, v85
	v_cvt_pk_bf16_f32 v91, v86, v87
	s_add_u32 s98, s98, 0x16000
	s_addc_u32 s99, s99, 0
	global_store_dwordx4 v250, v[88:91], s[98:99]
	v_fmamk_f32 v254, v245, 0x3a800000, v155
	v_rsq_f32_e32 v252, v254
	global_load_dword v245, v255, s[14:15] offset:192
; __device__ __forceinline__ unsigned cvt_pk_bf16(float lo, float hi) { unsigned r; asm volatile("v_cvt_pk_bf16_f32 %0, %1, %2" : "=v"(r) : "v"(lo), "v"(hi)); return r; }
;     __device__ __forceinline__ void operator()(const f32x4 (&acc)[2][2][4][2], const Unit& u, int wr, int wc, int fr, int fq) const {
;         const int col = u.pn * 128 + wc * 32 + 8 * fq; const int row0 = u.pm * 256 + wr * 64 + fr;
;         float rsv[8];
; #pragma unroll
;         for (int i = 0; i < 8; ++i) rsv[i] = ssq[row0 + (i >> 2) * 128 + (i & 3) * 16];
; #pragma unroll
;         for (int ai = 0; ai < 2; ++ai)
; #pragma unroll
;             for (int m = 0; m < 4; ++m) { const int row = row0 + ai * 128 + m * 16; const float rs = rsqrtf(rsv[ai * 4 + m] * (1.f / D) + EPS); float h[8];
; #pragma unroll
;                 for (int j = 0; j < 8; ++j) { const float gv = acc[ai][0][m][j >> 2][j & 3] * rs, uv = acc[ai][1][m][j >> 2][j & 3] * rs; h[j] = gv / (1.f + __expf(-gv)) * uv; }
;                 u32x4 w; w.x = cvt_pk_bf16(h[0], h[1]); w.y = cvt_pk_bf16(h[2], h[3]); w.z = cvt_pk_bf16(h[4], h[5]); w.w = cvt_pk_bf16(h[6], h[7]);
;                 *(u32x4*)(H + (size_t)row * FF + col) = w; }
	v_pk_mul_f32 v[76:77], v[72:73], v[76:77]
	v_pk_mul_f32 v[78:79], v[74:75], v[78:79]
	v_pk_mul_f32 v[68:69], v[64:65], v[68:69]
	v_pk_mul_f32 v[70:71], v[66:67], v[70:71]
	v_mul_f32_e32 v252, 0xbfb8aa3b, v252
	v_pk_mul_f32 v[72:73], v[72:73], v[252:253] op_sel_hi:[1,0]
	v_pk_mul_f32 v[74:75], v[74:75], v[252:253] op_sel_hi:[1,0]
	v_pk_mul_f32 v[64:65], v[64:65], v[252:253] op_sel_hi:[1,0]
	v_pk_mul_f32 v[66:67], v[66:67], v[252:253] op_sel_hi:[1,0]
	v_exp_f32_e32 v72, v72
	v_exp_f32_e32 v73, v73
	v_exp_f32_e32 v74, v74
	v_exp_f32_e32 v75, v75
	v_exp_f32_e32 v64, v64
	v_exp_f32_e32 v65, v65
	v_exp_f32_e32 v66, v66
	v_exp_f32_e32 v67, v67
	v_pk_fma_f32 v[72:73], v[72:73], v[254:255], v[254:255] op_sel_hi:[1,0,0]
	v_pk_fma_f32 v[74:75], v[74:75], v[254:255], v[254:255] op_sel_hi:[1,0,0]
	v_pk_fma_f32 v[64:65], v[64:65], v[254:255], v[254:255] op_sel_hi:[1,0,0]
	v_pk_fma_f32 v[66:67], v[66:67], v[254:255], v[254:255] op_sel_hi:[1,0,0]
	v_rcp_f32_e32 v72, v72
	v_rcp_f32_e32 v73, v73
	v_rcp_f32_e32 v74, v74
	v_rcp_f32_e32 v75, v75
	v_rcp_f32_e32 v64, v64
	v_rcp_f32_e32 v65, v65
	v_rcp_f32_e32 v66, v66
	v_rcp_f32_e32 v67, v67
	v_pk_mul_f32 v[76:77], v[76:77], v[72:73]
	v_pk_mul_f32 v[78:79], v[78:79], v[74:75]
	v_pk_mul_f32 v[68:69], v[68:69], v[64:65]
	v_pk_mul_f32 v[70:71], v[70:71], v[66:67]
	v_cvt_pk_bf16_f32 v72, v76, v77
	v_cvt_pk_bf16_f32 v73, v78, v79
	v_cvt_pk_bf16_f32 v74, v68, v69
	v_cvt_pk_bf16_f32 v75, v70, v71
	s_add_u32 s98, s98, 0x16000
	s_addc_u32 s99, s99, 0
	global_store_dwordx4 v250, v[72:75], s[98:99]
	v_fmamk_f32 v254, v246, 0x3a800000, v155
	v_rsq_f32_e32 v252, v254
	global_load_dword v246, v255, s[14:15] offset:512
	v_pk_mul_f32 v[60:61], v[56:57], v[60:61]
	v_pk_mul_f32 v[62:63], v[58:59], v[62:63]
	v_pk_mul_f32 v[52:53], v[48:49], v[52:53]
	v_pk_mul_f32 v[54:55], v[50:51], v[54:55]
	v_mul_f32_e32 v252, 0xbfb8aa3b, v252
	v_pk_mul_f32 v[56:57], v[56:57], v[252:253] op_sel_hi:[1,0]
	v_pk_mul_f32 v[58:59], v[58:59], v[252:253] op_sel_hi:[1,0]
	v_pk_mul_f32 v[48:49], v[48:49], v[252:253] op_sel_hi:[1,0]
	v_pk_mul_f32 v[50:51], v[50:51], v[252:253] op_sel_hi:[1,0]
	v_exp_f32_e32 v56, v56
	v_exp_f32_e32 v57, v57
	v_exp_f32_e32 v58, v58
	v_exp_f32_e32 v59, v59
	v_exp_f32_e32 v48, v48
	v_exp_f32_e32 v49, v49
	v_exp_f32_e32 v50, v50
	v_exp_f32_e32 v51, v51
	v_pk_fma_f32 v[56:57], v[56:57], v[254:255], v[254:255] op_sel_hi:[1,0,0]
	v_pk_fma_f32 v[58:59], v[58:59], v[254:255], v[254:255] op_sel_hi:[1,0,0]
	v_pk_fma_f32 v[48:49], v[48:49], v[254:255], v[254:255] op_sel_hi:[1,0,0]
	v_pk_fma_f32 v[50:51], v[50:51], v[254:255], v[254:255] op_sel_hi:[1,0,0]
	v_rcp_f32_e32 v56, v56
	v_rcp_f32_e32 v57, v57
	v_rcp_f32_e32 v58, v58
	v_rcp_f32_e32 v59, v59
	v_rcp_f32_e32 v48, v48
	v_rcp_f32_e32 v49, v49
	v_rcp_f32_e32 v50, v50
	v_rcp_f32_e32 v51, v51
	v_pk_mul_f32 v[60:61], v[60:61], v[56:57]
	v_pk_mul_f32 v[62:63], v[62:63], v[58:59]
	v_pk_mul_f32 v[52:53], v[52:53], v[48:49]
	v_pk_mul_f32 v[54:55], v[54:55], v[50:51]
	v_cvt_pk_bf16_f32 v56, v60, v61
	v_cvt_pk_bf16_f32 v57, v62, v63
	v_cvt_pk_bf16_f32 v58, v52, v53
	v_cvt_pk_bf16_f32 v59, v54, v55
	s_add_u32 s98, s98, 0x6e000
	s_addc_u32 s99, s99, 0
	global_store_dwordx4 v250, v[56:59], s[98:99]
	v_fmamk_f32 v254, v247, 0x3a800000, v155
	v_rsq_f32_e32 v252, v254
	global_load_dword v247, v255, s[14:15] offset:576
	v_pk_mul_f32 v[44:45], v[40:41], v[44:45]
	v_pk_mul_f32 v[46:47], v[42:43], v[46:47]
	v_pk_mul_f32 v[36:37], v[32:33], v[36:37]
	v_pk_mul_f32 v[38:39], v[34:35], v[38:39]
	v_mul_f32_e32 v252, 0xbfb8aa3b, v252
	v_pk_mul_f32 v[40:41], v[40:41], v[252:253] op_sel_hi:[1,0]
	v_pk_mul_f32 v[42:43], v[42:43], v[252:253] op_sel_hi:[1,0]
	v_pk_mul_f32 v[32:33], v[32:33], v[252:253] op_sel_hi:[1,0]
	v_pk_mul_f32 v[34:35], v[34:35], v[252:253] op_sel_hi:[1,0]
	v_exp_f32_e32 v40, v40
	v_exp_f32_e32 v41, v41
	v_exp_f32_e32 v42, v42
	v_exp_f32_e32 v43, v43
	v_exp_f32_e32 v32, v32
	v_exp_f32_e32 v33, v33
	v_exp_f32_e32 v34, v34
	v_exp_f32_e32 v35, v35
	v_pk_fma_f32 v[40:41], v[40:41], v[254:255], v[254:255] op_sel_hi:[1,0,0]
	v_pk_fma_f32 v[42:43], v[42:43], v[254:255], v[254:255] op_sel_hi:[1,0,0]
; __device__ __forceinline__ unsigned cvt_pk_bf16(float lo, float hi) { unsigned r; asm volatile("v_cvt_pk_bf16_f32 %0, %1, %2" : "=v"(r) : "v"(lo), "v"(hi)); return r; }
;     __device__ __forceinline__ void operator()(const f32x4 (&acc)[2][2][4][2], const Unit& u, int wr, int wc, int fr, int fq) const {
;         const int col = u.pn * 128 + wc * 32 + 8 * fq; const int row0 = u.pm * 256 + wr * 64 + fr;
;         float rsv[8];
; #pragma unroll
;         for (int i = 0; i < 8; ++i) rsv[i] = ssq[row0 + (i >> 2) * 128 + (i & 3) * 16];
; #pragma unroll
;         for (int ai = 0; ai < 2; ++ai)
; #pragma unroll
;             for (int m = 0; m < 4; ++m) { const int row = row0 + ai * 128 + m * 16; const float rs = rsqrtf(rsv[ai * 4 + m] * (1.f / D) + EPS); float h[8];
; #pragma unroll
;                 for (int j = 0; j < 8; ++j) { const float gv = acc[ai][0][m][j >> 2][j & 3] * rs, uv = acc[ai][1][m][j >> 2][j & 3] * rs; h[j] = gv / (1.f + __expf(-gv)) * uv; }
;                 u32x4 w; w.x = cvt_pk_bf16(h[0], h[1]); w.y = cvt_pk_bf16(h[2], h[3]); w.z = cvt_pk_bf16(h[4], h[5]); w.w = cvt_pk_bf16(h[6], h[7]);
;                 *(u32x4*)(H + (size_t)row * FF + col) = w; }
	v_pk_fma_f32 v[32:33], v[32:33], v[254:255], v[254:255] op_sel_hi:[1,0,0]
	v_pk_fma_f32 v[34:35], v[34:35], v[254:255], v[254:255] op_sel_hi:[1,0,0]
	v_rcp_f32_e32 v40, v40
	v_rcp_f32_e32 v41, v41
	v_rcp_f32_e32 v42, v42
	v_rcp_f32_e32 v43, v43
	v_rcp_f32_e32 v32, v32
	v_rcp_f32_e32 v33, v33
	v_rcp_f32_e32 v34, v34
	v_rcp_f32_e32 v35, v35
	v_pk_mul_f32 v[44:45], v[44:45], v[40:41]
	v_pk_mul_f32 v[46:47], v[46:47], v[42:43]
	v_pk_mul_f32 v[36:37], v[36:37], v[32:33]
	v_pk_mul_f32 v[38:39], v[38:39], v[34:35]
	v_cvt_pk_bf16_f32 v40, v44, v45
	v_cvt_pk_bf16_f32 v41, v46, v47
	v_cvt_pk_bf16_f32 v42, v36, v37
	v_cvt_pk_bf16_f32 v43, v38, v39
	s_add_u32 s98, s98, 0x16000
	s_addc_u32 s99, s99, 0
	global_store_dwordx4 v250, v[40:43], s[98:99]
	v_fmamk_f32 v254, v248, 0x3a800000, v155
	v_rsq_f32_e32 v252, v254
	global_load_dword v248, v255, s[14:15] offset:640
	v_pk_mul_f32 v[28:29], v[24:25], v[28:29]
	v_pk_mul_f32 v[30:31], v[26:27], v[30:31]
	v_pk_mul_f32 v[20:21], v[16:17], v[20:21]
	v_pk_mul_f32 v[22:23], v[18:19], v[22:23]
	v_mul_f32_e32 v252, 0xbfb8aa3b, v252
	v_pk_mul_f32 v[24:25], v[24:25], v[252:253] op_sel_hi:[1,0]
	v_pk_mul_f32 v[26:27], v[26:27], v[252:253] op_sel_hi:[1,0]
	v_pk_mul_f32 v[16:17], v[16:17], v[252:253] op_sel_hi:[1,0]
	v_pk_mul_f32 v[18:19], v[18:19], v[252:253] op_sel_hi:[1,0]
	v_exp_f32_e32 v24, v24
	v_exp_f32_e32 v25, v25
	v_exp_f32_e32 v26, v26
	v_exp_f32_e32 v27, v27
	v_exp_f32_e32 v16, v16
	v_exp_f32_e32 v17, v17
	v_exp_f32_e32 v18, v18
	v_exp_f32_e32 v19, v19
	v_pk_fma_f32 v[24:25], v[24:25], v[254:255], v[254:255] op_sel_hi:[1,0,0]
	v_pk_fma_f32 v[26:27], v[26:27], v[254:255], v[254:255] op_sel_hi:[1,0,0]
	v_pk_fma_f32 v[16:17], v[16:17], v[254:255], v[254:255] op_sel_hi:[1,0,0]
	v_pk_fma_f32 v[18:19], v[18:19], v[254:255], v[254:255] op_sel_hi:[1,0,0]
	v_rcp_f32_e32 v24, v24
	v_rcp_f32_e32 v25, v25
	v_rcp_f32_e32 v26, v26
	v_rcp_f32_e32 v27, v27
	v_rcp_f32_e32 v16, v16
	v_rcp_f32_e32 v17, v17
	v_rcp_f32_e32 v18, v18
	v_rcp_f32_e32 v19, v19
	v_pk_mul_f32 v[28:29], v[28:29], v[24:25]
	v_pk_mul_f32 v[30:31], v[30:31], v[26:27]
	v_pk_mul_f32 v[20:21], v[20:21], v[16:17]
	v_pk_mul_f32 v[22:23], v[22:23], v[18:19]
	v_cvt_pk_bf16_f32 v24, v28, v29
	v_cvt_pk_bf16_f32 v25, v30, v31
	v_cvt_pk_bf16_f32 v26, v20, v21
	v_cvt_pk_bf16_f32 v27, v22, v23
	s_add_u32 s98, s98, 0x16000
	s_addc_u32 s99, s99, 0
	global_store_dwordx4 v250, v[24:27], s[98:99]
	v_fmamk_f32 v254, v249, 0x3a800000, v155
	v_rsq_f32_e32 v252, v254
	global_load_dword v249, v255, s[14:15] offset:704
	v_pk_mul_f32 v[12:13], v[8:9], v[12:13]
	v_pk_mul_f32 v[14:15], v[10:11], v[14:15]
	v_pk_mul_f32 v[0:1], v[4:5], v[0:1]
	v_pk_mul_f32 v[2:3], v[6:7], v[2:3]
	v_mul_f32_e32 v252, 0xbfb8aa3b, v252
	v_pk_mul_f32 v[8:9], v[8:9], v[252:253] op_sel_hi:[1,0]
	v_pk_mul_f32 v[10:11], v[10:11], v[252:253] op_sel_hi:[1,0]
	v_pk_mul_f32 v[4:5], v[4:5], v[252:253] op_sel_hi:[1,0]
	v_pk_mul_f32 v[6:7], v[6:7], v[252:253] op_sel_hi:[1,0]
	v_exp_f32_e32 v8, v8
	v_exp_f32_e32 v9, v9
	v_exp_f32_e32 v10, v10
	v_exp_f32_e32 v11, v11
	v_exp_f32_e32 v4, v4
	v_exp_f32_e32 v5, v5
	v_exp_f32_e32 v6, v6
	v_exp_f32_e32 v7, v7
	v_pk_fma_f32 v[8:9], v[8:9], v[254:255], v[254:255] op_sel_hi:[1,0,0]
	v_pk_fma_f32 v[10:11], v[10:11], v[254:255], v[254:255] op_sel_hi:[1,0,0]
	v_pk_fma_f32 v[4:5], v[4:5], v[254:255], v[254:255] op_sel_hi:[1,0,0]
	v_pk_fma_f32 v[6:7], v[6:7], v[254:255], v[254:255] op_sel_hi:[1,0,0]
	v_rcp_f32_e32 v8, v8
	v_rcp_f32_e32 v9, v9
	v_rcp_f32_e32 v10, v10
	v_rcp_f32_e32 v11, v11
	v_rcp_f32_e32 v4, v4
	v_rcp_f32_e32 v5, v5
	v_rcp_f32_e32 v6, v6
	v_rcp_f32_e32 v7, v7
	v_pk_mul_f32 v[12:13], v[12:13], v[8:9]
	v_pk_mul_f32 v[14:15], v[14:15], v[10:11]
	v_pk_mul_f32 v[0:1], v[0:1], v[4:5]
	v_pk_mul_f32 v[2:3], v[2:3], v[6:7]
	v_cvt_pk_bf16_f32 v8, v12, v13
	v_cvt_pk_bf16_f32 v9, v14, v15
	v_cvt_pk_bf16_f32 v10, v0, v1
	v_cvt_pk_bf16_f32 v11, v2, v3
	s_add_u32 s98, s98, 0x16000
	s_addc_u32 s99, s99, 0
	global_store_dwordx4 v250, v[8:11], s[98:99]
	s_and_b64 vcc, exec, s[6:7]
	s_mov_b64 s[0:1], -1
	s_cbranch_vccnz .LBB0_1594
	s_andn2_b64 vcc, exec, s[20:21]
	s_cbranch_vccnz .LBB0_1593
	s_barrier
	s_branch .LBB0_1593

; __global__ void __launch_bounds__(512, 2) fwd_kernel(Args a) {
	.amdhsa_kernel _Z10fwd_kernel4Args
		.amdhsa_group_segment_fixed_size 0
		.amdhsa_private_segment_fixed_size 0
		.amdhsa_kernarg_size 464
		.amdhsa_user_sgpr_count 2
		.amdhsa_user_sgpr_dispatch_ptr 0
		.amdhsa_user_sgpr_queue_ptr 0
		.amdhsa_user_sgpr_kernarg_segment_ptr 1
		.amdhsa_user_sgpr_dispatch_id 0
		.amdhsa_user_sgpr_kernarg_preload_length 0
		.amdhsa_user_sgpr_kernarg_preload_offset 0
		.amdhsa_user_sgpr_private_segment_size 0
		.amdhsa_uses_dynamic_stack 0
		.amdhsa_enable_private_segment 0
		.amdhsa_system_sgpr_workgroup_id_x 1
		.amdhsa_system_sgpr_workgroup_id_y 0
		.amdhsa_system_sgpr_workgroup_id_z 0
		.amdhsa_system_sgpr_workgroup_info 0
		.amdhsa_system_vgpr_workitem_id 2
		.amdhsa_next_free_vgpr 256
		.amdhsa_next_free_sgpr 102
		.amdhsa_accum_offset 256
		.amdhsa_reserve_vcc 1
		.amdhsa_float_round_mode_32 0
		.amdhsa_float_round_mode_16_64 0
		.amdhsa_float_denorm_mode_32 3
		.amdhsa_float_denorm_mode_16_64 3
		.amdhsa_dx10_clamp 1
		.amdhsa_ieee_mode 1
		.amdhsa_fp16_overflow 0
		.amdhsa_tg_split 0
		.amdhsa_exception_fp_ieee_invalid_op 0
		.amdhsa_exception_fp_denorm_src 0
		.amdhsa_exception_fp_ieee_div_zero 0
		.amdhsa_exception_fp_ieee_overflow 0
		.amdhsa_exception_fp_ieee_underflow 0
		.amdhsa_exception_fp_ieee_inexact 0
		.amdhsa_exception_int_div_zero 0
	.end_amdhsa_kernel

; __global__ void __launch_bounds__(512, 2) fwd_kernel(Args a) {
amdhsa.kernels:
  - .agpr_count:     0
    .args:
      - .offset:         0
        .size:           208
        .value_kind:     by_value
      - .offset:         208
        .size:           4
        .value_kind:     hidden_block_count_x
      - .offset:         212
        .size:           4
        .value_kind:     hidden_block_count_y
      - .offset:         216
        .size:           4
        .value_kind:     hidden_block_count_z
      - .offset:         220
        .size:           2
        .value_kind:     hidden_group_size_x
      - .offset:         222
        .size:           2
        .value_kind:     hidden_group_size_y
      - .offset:         224
        .size:           2
        .value_kind:     hidden_group_size_z
      - .offset:         226
        .size:           2
        .value_kind:     hidden_remainder_x
      - .offset:         228
        .size:           2
        .value_kind:     hidden_remainder_y
      - .offset:         230
        .size:           2
        .value_kind:     hidden_remainder_z
      - .offset:         248
        .size:           8
        .value_kind:     hidden_global_offset_x
      - .offset:         256
        .size:           8
        .value_kind:     hidden_global_offset_y
      - .offset:         264
        .size:           8
        .value_kind:     hidden_global_offset_z
      - .offset:         272
        .size:           2
        .value_kind:     hidden_grid_dims
      - .offset:         296
        .size:           8
        .value_kind:     hidden_multigrid_sync_arg
      - .offset:         328
        .size:           4
        .value_kind:     hidden_dynamic_lds_size
    .group_segment_fixed_size: 0
    .kernarg_segment_align: 8
    .kernarg_segment_size: 464
    .language:       OpenCL C
    .language_version:
      - 2
      - 0
    .max_flat_workgroup_size: 512
    .name:           _Z10fwd_kernel4Args
    .private_segment_fixed_size: 0
    .sgpr_count:     108
    .sgpr_spill_count: 57
    .symbol:         _Z10fwd_kernel4Args.kd
    .uniform_work_group_size: 1
    .uses_dynamic_stack: false
    .vgpr_count:     256
    .vgpr_spill_count: 0
    .wavefront_size: 64
